# fold phase meta-token dot: issue the 7 serialized weight-load pairs up front with counted vmcnt waits (single accumulator rename), on top of v45
# baseline (speedup 1.0000x reference)
; __device__ __forceinline__ bf16_t f2bf(float f) { return (bf16_t)(cvt_pk_bf16(f, 0.f) & 0xffffu); }
; __device__ __forceinline__ int otid() { int t = threadIdx.x; asm volatile("" : "+v"(t)); return t; }
; __device__ void conv_mixer_item(const Params& p, int l, int it, float* lds) {
;     ...
;         const int kb = it & 1, jb = it >> 1, k = kb * 512 + otid();
;         const float* src = p.w_in + (size_t)l * 1024 * 4112 + (size_t)k * 4112 + 2048; float a[16];
; #pragma unroll
;         for (int q = 0; q < 4; ++q) { const f32x4 v = *(const f32x4*)(src + 4 * q); a[4 * q] = v[0]; a[4 * q + 1] = v[1]; a[4 * q + 2] = v[2]; a[4 * q + 3] = v[3]; }
;         const float* wa = p.w_alpha + (size_t)l * 16 * 256; const float g1 = p.norm1[(size_t)l * DM + k];
;         for (int jj = 0; jj < 8; ++jj) { const int j = jb * 8 + jj; float s = 0.f;
; #pragma unroll
;             for (int r = 0; r < 16; ++r) s += a[r] * wa[r * 256 + j];
;             W[W_IN + (size_t)(C_GL + j) * 1024 + k] = f2bf(s * g1); }
.LBB0_146:
	s_and_b64 vcc, exec, s[40:41]
	s_cbranch_vccz .LBB0_148
	v_mov_b32_e32 v0, v228
	s_and_b32 s22, s10, 0x200
	s_and_b32 s33, s12, 0x7f8
	v_add_u32_e32 v10, s22, v0
	v_ashrrev_i32_e32 v11, 31, v10
	s_waitcnt lgkmcnt(0)
	v_lshl_add_u64 v[2:3], v[10:11], 2, s[68:69]
	global_load_dword v0, v[2:3], off
	v_mov_b64_e32 v[2:3], s[88:89]
	s_movk_i32 s22, 0x4040
	v_mad_i64_i32 v[2:3], s[22:23], v10, s22, v[2:3]
	s_mov_b64 s[22:23], 0x2000
	s_nop 0
	v_lshl_add_u64 v[6:7], v[2:3], 0, s[22:23]
	v_add_co_u32_e32 v2, vcc, 0x2000, v2
	s_lshl_b32 s22, s33, 2
	s_nop 0
	v_addc_co_u32_e32 v3, vcc, 0, v3, vcc
	global_load_dwordx4 v[42:45], v[2:3], off
	global_load_dwordx4 v[38:41], v[6:7], off offset:16
	s_nop 0
	global_load_dwordx4 v[2:5], v[6:7], off offset:32
	s_nop 0
	global_load_dwordx4 v[6:9], v[6:7], off offset:48
	s_add_u32 s40, s6, s22
	s_addc_u32 s41, s7, 0
	s_add_i32 s30, s33, 0x400
	v_lshl_add_u64 v[98:99], v[10:11], 1, s[18:19]
	s_waitcnt vmcnt(0)
	v_mov_b32_e32 v106, v45
	v_mov_b32_e32 v104, v41
	v_mov_b32_e32 v102, v5
	v_mov_b32_e32 v5, s22
	global_load_dwordx4 v[46:49], v5, s[6:7] offset:-4080
	global_load_dwordx4 v[76:79], v5, s[6:7] offset:-4096
	global_load_dwordx4 v[50:53], v5, s[6:7] offset:-3056
	global_load_dwordx4 v[80:83], v5, s[6:7] offset:-3072
	global_load_dwordx4 v[58:61], v5, s[6:7] offset:-2032
	global_load_dwordx4 v[86:89], v5, s[6:7] offset:-2048
	global_load_dwordx4 v[66:69], v5, s[6:7] offset:-1008
	global_load_dwordx4 v[90:93], v5, s[6:7] offset:-1024
	global_load_dwordx4 v[108:111], v5, s[6:7]
	global_load_dwordx4 v[54:57], v5, s[6:7] offset:1040
	global_load_dwordx4 v[112:115], v5, s[6:7] offset:1024
	global_load_dwordx4 v[62:65], v5, s[6:7] offset:2064
	global_load_dwordx4 v[116:119], v5, s[6:7] offset:2048
	s_lshl_b32 s22, s30, 2
	global_load_dwordx4 v[70:73], v5, s[6:7] offset:3088
	global_load_dwordx4 v[120:123], v5, s[6:7] offset:3072
	v_mov_b32_e32 v5, s22
	global_load_dwordx2 v[142:143], v5, s[6:7]
	s_add_u32 s22, s40, 0x1400
	s_addc_u32 s23, s41, 0
	v_mov_b32_e32 v100, v9
	global_load_dwordx4 v[10:13], v1, s[22:23] offset:16
	global_load_dwordx4 v[144:147], v230, s[40:41] offset:1024
	s_add_u32 s22, s40, 0x1800
	s_addc_u32 s23, s41, 0
	global_load_dwordx4 v[14:17], v1, s[22:23] offset:16
	global_load_dwordx4 v[148:151], v230, s[40:41] offset:2048
	s_add_u32 s22, s40, 0x1c00
	s_addc_u32 s23, s41, 0
	global_load_dwordx4 v[18:21], v1, s[22:23] offset:16
	global_load_dwordx4 v[94:97], v230, s[40:41] offset:3072
	s_add_u32 s22, s40, 0x2000
	s_addc_u32 s23, s41, 0
	global_load_dwordx4 v[22:25], v1, s[22:23] offset:16
	global_load_dwordx4 v[124:127], v231, s[40:41]
	s_add_u32 s22, s40, 0x2400
	s_addc_u32 s23, s41, 0
	global_load_dwordx4 v[26:29], v1, s[22:23] offset:16
	global_load_dwordx4 v[128:131], v231, s[40:41] offset:1024
	s_add_u32 s22, s40, 0x2800
	s_addc_u32 s23, s41, 0
	global_load_dwordx4 v[30:33], v1, s[22:23] offset:16
	global_load_dwordx4 v[132:135], v231, s[40:41] offset:2048
	s_add_u32 s22, s40, 0x2c00
	s_addc_u32 s23, s41, 0
	global_load_dwordx4 v[34:37], v1, s[22:23] offset:16
	global_load_dwordx4 v[136:139], v231, s[40:41] offset:3072
	s_waitcnt vmcnt(29)
	v_pk_fma_f32 v[46:47], v[42:43], v[46:47], 0 op_sel_hi:[0,1,0]
	s_waitcnt vmcnt(28)
	v_pk_fma_f32 v[140:141], v[42:43], v[76:77], 0 op_sel_hi:[0,1,0]
	s_waitcnt vmcnt(26)
	v_pk_fma_f32 v[140:141], v[42:43], v[80:81], v[140:141] op_sel:[1,0,0]
	v_pk_fma_f32 v[46:47], v[42:43], v[50:51], v[46:47] op_sel:[1,0,0]
	s_waitcnt vmcnt(24)
	v_pk_fma_f32 v[140:141], v[44:45], v[86:87], v[140:141] op_sel_hi:[0,1,1]
	s_waitcnt vmcnt(22)
	v_pk_fma_f32 v[140:141], v[106:107], v[90:91], v[140:141] op_sel_hi:[0,1,1]
	s_waitcnt vmcnt(21)
	v_pk_fma_f32 v[140:141], v[38:39], v[108:109], v[140:141] op_sel_hi:[0,1,1]
	s_waitcnt vmcnt(19)
	v_pk_fma_f32 v[140:141], v[38:39], v[112:113], v[140:141] op_sel:[1,0,0]
	v_pk_fma_f32 v[46:47], v[44:45], v[58:59], v[46:47] op_sel_hi:[0,1,1]
	s_waitcnt vmcnt(17)
	v_pk_fma_f32 v[140:141], v[40:41], v[116:117], v[140:141] op_sel_hi:[0,1,1]
	s_waitcnt vmcnt(15)
	v_pk_fma_f32 v[140:141], v[104:105], v[120:121], v[140:141] op_sel_hi:[0,1,1]
	s_waitcnt vmcnt(14)
	v_pk_fma_f32 v[140:141], v[2:3], v[142:143], v[140:141] op_sel_hi:[0,1,1]
	v_pk_fma_f32 v[46:47], v[106:107], v[66:67], v[46:47] op_sel_hi:[0,1,1]
	s_waitcnt vmcnt(12)
	v_pk_fma_f32 v[140:141], v[2:3], v[144:145], v[140:141] op_sel:[1,0,0]
	s_waitcnt vmcnt(10)
	v_pk_fma_f32 v[140:141], v[4:5], v[148:149], v[140:141] op_sel_hi:[0,1,1]
	s_waitcnt vmcnt(8)
	v_pk_fma_f32 v[140:141], v[102:103], v[94:95], v[140:141] op_sel_hi:[0,1,1]
	s_waitcnt vmcnt(6)
	v_pk_fma_f32 v[140:141], v[6:7], v[124:125], v[140:141] op_sel_hi:[0,1,1]
	s_waitcnt vmcnt(4)
	v_pk_fma_f32 v[140:141], v[6:7], v[128:129], v[140:141] op_sel:[1,0,0]
	s_lshl_b32 s86, s30, 11
	s_waitcnt vmcnt(2)
	v_pk_fma_f32 v[140:141], v[8:9], v[132:133], v[140:141] op_sel_hi:[0,1,1]
	s_lshl_b32 s40, s33, 11
	s_add_i32 s22, s40, 0x200800
	s_mov_b32 s23, s87
	v_lshl_add_u64 v[80:81], v[98:99], 0, s[22:23]
	s_add_i32 s23, s33, 0x402
	s_lshl_b32 s22, s23, 2
	s_waitcnt vmcnt(0)
; __device__ __forceinline__ bf16_t f2bf(float f) { return (bf16_t)(cvt_pk_bf16(f, 0.f) & 0xffffu); }
; __device__ void conv_mixer_item(const Params& p, int l, int it, float* lds) {
;     ...
;         const float* wa = p.w_alpha + (size_t)l * 16 * 256; const float g1 = p.norm1[(size_t)l * DM + k];
;         for (int jj = 0; jj < 8; ++jj) { const int j = jb * 8 + jj; float s = 0.f;
; #pragma unroll
;             for (int r = 0; r < 16; ++r) s += a[r] * wa[r * 256 + j];
;             W[W_IN + (size_t)(C_GL + j) * 1024 + k] = f2bf(s * g1); }
	v_pk_fma_f32 v[74:75], v[100:101], v[136:137], v[140:141] op_sel_hi:[0,1,1]
	v_pk_mul_f32 v[74:75], v[0:1], v[74:75] op_sel_hi:[0,1]
	v_cvt_pk_bf16_f32 v5, v74, v75
	v_lshl_add_u64 v[74:75], v[98:99], 0, s[86:87]
	global_store_short v[74:75], v5, off
	global_store_short_d16_hi v[80:81], v5, off
	v_mov_b32_e32 v5, s22
	v_pk_fma_f32 v[74:75], v[42:43], v[78:79], 0 op_sel_hi:[0,1,0]
	global_load_dwordx2 v[78:79], v5, s[6:7]
	v_pk_fma_f32 v[74:75], v[42:43], v[82:83], v[74:75] op_sel:[1,0,0]
	s_lshl_b32 s86, s23, 11
	v_pk_fma_f32 v[74:75], v[44:45], v[88:89], v[74:75] op_sel_hi:[0,1,1]
	v_pk_fma_f32 v[74:75], v[106:107], v[92:93], v[74:75] op_sel_hi:[0,1,1]
	v_pk_fma_f32 v[74:75], v[38:39], v[110:111], v[74:75] op_sel_hi:[0,1,1]
	v_pk_fma_f32 v[74:75], v[38:39], v[114:115], v[74:75] op_sel:[1,0,0]
	s_add_i32 s22, s40, 0x201800
	v_pk_fma_f32 v[74:75], v[40:41], v[118:119], v[74:75] op_sel_hi:[0,1,1]
	v_pk_fma_f32 v[74:75], v[104:105], v[122:123], v[74:75] op_sel_hi:[0,1,1]
	s_mov_b32 s23, s87
	s_waitcnt vmcnt(0)
	v_pk_fma_f32 v[74:75], v[2:3], v[78:79], v[74:75] op_sel_hi:[0,1,1]
	v_pk_fma_f32 v[74:75], v[2:3], v[146:147], v[74:75] op_sel:[1,0,0]
	v_lshl_add_u64 v[76:77], v[98:99], 0, s[22:23]
	v_pk_fma_f32 v[74:75], v[4:5], v[150:151], v[74:75] op_sel_hi:[0,1,1]
	v_pk_fma_f32 v[74:75], v[102:103], v[96:97], v[74:75] op_sel_hi:[0,1,1]
	v_pk_fma_f32 v[74:75], v[6:7], v[126:127], v[74:75] op_sel_hi:[0,1,1]
	v_pk_fma_f32 v[74:75], v[6:7], v[130:131], v[74:75] op_sel:[1,0,0]
	s_nop 0
	v_pk_fma_f32 v[74:75], v[8:9], v[134:135], v[74:75] op_sel_hi:[0,1,1]
	v_pk_fma_f32 v[74:75], v[100:101], v[138:139], v[74:75] op_sel_hi:[0,1,1]
	v_pk_mul_f32 v[74:75], v[0:1], v[74:75] op_sel_hi:[0,1]
	v_cvt_pk_bf16_f32 v5, v74, v75
	v_lshl_add_u64 v[74:75], v[98:99], 0, s[86:87]
	s_or_b32 s86, s12, 4
	s_lshl_b64 s[22:23], s[86:87], 2
	s_add_u32 s22, s6, s22
	global_store_short v[74:75], v5, off
	global_store_short_d16_hi v[76:77], v5, off
	s_addc_u32 s23, s7, s23
	global_load_dwordx2 v[50:51], v1, s[22:23]
	s_add_i32 s23, s33, 0x404
	s_lshl_b32 s22, s23, 2
	v_mov_b32_e32 v5, s22
	s_lshl_b32 s86, s23, 11
	s_add_i32 s22, s40, 0x202800
	s_mov_b32 s23, s87
	s_waitcnt vmcnt(0)
	v_pk_fma_f32 v[46:47], v[38:39], v[50:51], v[46:47] op_sel_hi:[0,1,1]
	global_load_dwordx2 v[50:51], v5, s[6:7]
	v_pk_fma_f32 v[46:47], v[38:39], v[54:55], v[46:47] op_sel:[1,0,0]
	s_nop 0
	v_pk_fma_f32 v[46:47], v[40:41], v[62:63], v[46:47] op_sel_hi:[0,1,1]
	v_pk_fma_f32 v[46:47], v[104:105], v[70:71], v[46:47] op_sel_hi:[0,1,1]
	s_waitcnt vmcnt(0)
	v_pk_fma_f32 v[46:47], v[2:3], v[50:51], v[46:47] op_sel_hi:[0,1,1]
	v_pk_fma_f32 v[10:11], v[2:3], v[10:11], v[46:47] op_sel:[1,0,0]
	s_nop 0
	v_pk_fma_f32 v[10:11], v[4:5], v[14:15], v[10:11] op_sel_hi:[0,1,1]
	v_pk_fma_f32 v[10:11], v[102:103], v[18:19], v[10:11] op_sel_hi:[0,1,1]
	v_pk_fma_f32 v[10:11], v[6:7], v[22:23], v[10:11] op_sel_hi:[0,1,1]
	v_pk_fma_f32 v[10:11], v[6:7], v[26:27], v[10:11] op_sel:[1,0,0]
	v_lshl_add_u64 v[14:15], v[98:99], 0, s[22:23]
	v_pk_fma_f32 v[10:11], v[8:9], v[30:31], v[10:11] op_sel_hi:[0,1,1]
	v_pk_fma_f32 v[10:11], v[100:101], v[34:35], v[10:11] op_sel_hi:[0,1,1]
	v_pk_mul_f32 v[10:11], v[0:1], v[10:11] op_sel_hi:[0,1]
	v_cvt_pk_bf16_f32 v5, v10, v11
	v_lshl_add_u64 v[10:11], v[98:99], 0, s[86:87]
	s_or_b32 s86, s12, 6
	s_lshl_b64 s[22:23], s[86:87], 2
	s_add_u32 s22, s6, s22
	global_store_short v[10:11], v5, off
	global_store_short_d16_hi v[14:15], v5, off
	s_addc_u32 s23, s7, s23
	global_load_dwordx2 v[14:15], v1, s[22:23]
	v_pk_fma_f32 v[10:11], v[42:43], v[48:49], 0 op_sel_hi:[0,1,0]
	v_pk_fma_f32 v[10:11], v[42:43], v[52:53], v[10:11] op_sel:[1,0,0]
	s_addk_i32 s33, 0x406
	v_pk_fma_f32 v[10:11], v[44:45], v[60:61], v[10:11] op_sel_hi:[0,1,1]
	s_lshl_b32 s22, s33, 2
	v_pk_fma_f32 v[10:11], v[106:107], v[68:69], v[10:11] op_sel_hi:[0,1,1]
	v_mov_b32_e32 v5, s22
	s_lshl_b32 s86, s33, 11
	s_add_i32 s22, s40, 0x203800
	s_mov_b32 s23, s87
	s_waitcnt vmcnt(0)
	v_pk_fma_f32 v[10:11], v[38:39], v[14:15], v[10:11] op_sel_hi:[0,1,1]
	global_load_dwordx2 v[14:15], v5, s[6:7]
	v_pk_fma_f32 v[10:11], v[38:39], v[56:57], v[10:11] op_sel:[1,0,0]
	s_nop 0
	v_pk_fma_f32 v[10:11], v[40:41], v[64:65], v[10:11] op_sel_hi:[0,1,1]
	v_pk_fma_f32 v[10:11], v[104:105], v[72:73], v[10:11] op_sel_hi:[0,1,1]
	s_waitcnt vmcnt(0)
	v_pk_fma_f32 v[10:11], v[2:3], v[14:15], v[10:11] op_sel_hi:[0,1,1]
	v_pk_fma_f32 v[2:3], v[2:3], v[12:13], v[10:11] op_sel:[1,0,0]
	s_nop 0
	v_pk_fma_f32 v[2:3], v[4:5], v[16:17], v[2:3] op_sel_hi:[0,1,1]
	v_pk_fma_f32 v[2:3], v[102:103], v[20:21], v[2:3] op_sel_hi:[0,1,1]
	v_pk_fma_f32 v[2:3], v[6:7], v[24:25], v[2:3] op_sel_hi:[0,1,1]
	v_pk_fma_f32 v[2:3], v[6:7], v[28:29], v[2:3] op_sel:[1,0,0]
	v_lshl_add_u64 v[4:5], v[98:99], 0, s[22:23]
	v_pk_fma_f32 v[2:3], v[8:9], v[32:33], v[2:3] op_sel_hi:[0,1,1]
	v_pk_fma_f32 v[2:3], v[100:101], v[36:37], v[2:3] op_sel_hi:[0,1,1]
	v_pk_mul_f32 v[2:3], v[0:1], v[2:3] op_sel_hi:[0,1]
	v_cvt_pk_bf16_f32 v0, v2, v3
	v_lshl_add_u64 v[2:3], v[98:99], 0, s[86:87]
	global_store_short v[2:3], v0, off
	global_store_short_d16_hi v[4:5], v0, off
